# prologue modulation GEMV: rolling reload of each row quad right after its FMAs (8 loads in flight through an item instead of draining every 8 rows)
# baseline (speedup 1.0000x reference)
; __device__ __forceinline__ void p0a(Frame& F, const Args& AR) {
;     ...
;         for (int it = F.bid; it < DEPTH * 9 * MOD_CHUNKS; it += F.G) {
;             const int ch = it % MOD_CHUNKS, lj = it / MOD_CHUNKS, jg = lj % 9, l = lj / 9;
;             const float* wp = AR.in[I_WMOD] + ((size_t)l * DM + (size_t)ch * DCH) * MODW + jg * 2048 + F.tid * 4;
;             f32x4 a0 = {0.f, 0.f, 0.f, 0.f}, a1 = a0, a2 = a0;
; #pragma unroll 8
;             for (int d = 0; d < DCH; ++d) { const f32x4 w = __builtin_nontemporal_load((const f32x4*)(wp + (size_t)d * MODW)); const int dd = ch * DCH + d;
;                 a0 += w * sv[dd]; a1 += w * sv[DM + dd]; a2 += w * sv[2 * DM + dd]; }
;             float* o = modp + ((size_t)(ch * DEPTH + l) * 3) * MODW + jg * 2048 + F.tid * 4;
;             *(f32x4*)(o) = a0; *(f32x4*)(o + MODW) = a1; *(f32x4*)(o + 2 * MODW) = a2;
.LBB0_29:
	s_ashr_i32 s0, s15, 31
	s_lshr_b32 s0, s0, 27
	s_add_i32 s0, s15, s0
	s_ashr_i32 s1, s0, 5
	s_andn2_b32 s0, s0, 31
	s_sub_i32 s16, s15, s0
	s_mul_hi_i32 s0, s1, 0x38e38e39
	s_lshr_b32 s4, s0, 31
	s_lshr_b32 s0, s0, 1
	s_add_i32 s0, s0, s4
	s_mul_i32 s0, s0, 9
	s_sub_i32 s0, s1, s0
	s_mul_hi_i32 s1, s15, 0x38e38e39
	s_lshr_b32 s4, s1, 31
	s_ashr_i32 s17, s1, 6
	s_add_i32 s17, s17, s4
	s_mul_i32 s5, s16, 0x480000
	v_readlane_b32 s36, v250, 2
	s_mul_i32 s4, s17, 0x9000000
	s_ashr_i32 s18, s5, 31
	v_readlane_b32 s44, v250, 10
	s_mul_hi_i32 s1, s17, 0x9000000
	v_readlane_b32 s45, v250, 11
	s_add_u32 s4, s44, s4
	s_addc_u32 s1, s45, s1
	s_add_u32 s4, s4, s5
	s_addc_u32 s5, s1, s18
	s_lshl_b32 s0, s0, 11
	s_ashr_i32 s1, s0, 31
	s_lshl_b64 s[0:1], s[0:1], 2
	s_add_u32 s4, s4, s0
	s_addc_u32 s5, s5, s1
	v_lshl_add_u64 v[16:17], v[14:15], 2, s[4:5]
	s_lshl_b32 s4, s16, 8
	v_mov_b32_e32 v6, 0
	s_add_i32 s18, s4, 0
	s_mov_b64 s[4:5], 0
	v_mov_b32_e32 v7, v6
	v_mov_b32_e32 v8, v6
	v_mov_b32_e32 v9, v6
	v_mov_b32_e32 v10, v6
	v_mov_b32_e32 v11, v6
	v_mov_b32_e32 v12, v6
	v_mov_b32_e32 v13, v6
	v_mov_b32_e32 v2, v6
	v_mov_b32_e32 v3, v6
	v_mov_b32_e32 v4, v6
	v_mov_b32_e32 v5, v6
	v_readlane_b32 s37, v250, 3
	v_readlane_b32 s38, v250, 4
	v_readlane_b32 s39, v250, 5
	v_readlane_b32 s40, v250, 6
	v_readlane_b32 s41, v250, 7
	v_readlane_b32 s42, v250, 8
	v_readlane_b32 s43, v250, 9
	v_readlane_b32 s46, v250, 12
	v_readlane_b32 s47, v250, 13
	v_readlane_b32 s48, v250, 14
	v_readlane_b32 s49, v250, 15
	v_readlane_b32 s50, v250, 16
	v_readlane_b32 s51, v250, 17
	v_lshl_add_u64 v[96:97], v[16:17], 0, s[4:5]
	v_add_co_u32_e32 v98, vcc, s8, v96
	s_nop 1
	v_addc_co_u32_e32 v99, vcc, 0, v97, vcc
	v_add_co_u32_e32 v100, vcc, s9, v96
	s_nop 1
	v_addc_co_u32_e32 v101, vcc, 0, v97, vcc
	v_add_co_u32_e32 v102, vcc, s10, v96
	s_nop 1
	v_addc_co_u32_e32 v103, vcc, 0, v97, vcc
	v_add_co_u32_e32 v104, vcc, s11, v96
	s_nop 1
	v_addc_co_u32_e32 v105, vcc, 0, v97, vcc
	v_add_co_u32_e32 v106, vcc, s12, v96
	s_nop 1
	v_addc_co_u32_e32 v107, vcc, 0, v97, vcc
	v_add_co_u32_e32 v108, vcc, s13, v96
	s_nop 1
	v_addc_co_u32_e32 v109, vcc, 0, v97, vcc
	v_add_co_u32_e32 v110, vcc, s14, v96
	s_nop 1
	v_addc_co_u32_e32 v111, vcc, 0, v97, vcc
	global_load_dwordx4 v[18:21], v[96:97], off nt
	global_load_dwordx4 v[22:25], v[98:99], off nt
	global_load_dwordx4 v[26:29], v[100:101], off nt
	global_load_dwordx4 v[30:33], v[102:103], off nt
	global_load_dwordx4 v[34:37], v[104:105], off nt
	global_load_dwordx4 v[38:41], v[106:107], off nt
	global_load_dwordx4 v[42:45], v[108:109], off nt
	global_load_dwordx4 v[46:49], v[110:111], off nt
.LBB0_30:
	s_add_u32 s4, s4, 0x90000
	s_addc_u32 s5, s5, 0
	s_cmp_eq_u32 s4, 0x480000
	s_cbranch_scc1 .Lgemv_tail
	v_lshl_add_u64 v[96:97], v[16:17], 0, s[4:5]
	v_add_co_u32_e32 v98, vcc, s8, v96
	s_nop 1
	v_addc_co_u32_e32 v99, vcc, 0, v97, vcc
	v_add_co_u32_e32 v100, vcc, s9, v96
	s_nop 1
	v_addc_co_u32_e32 v101, vcc, 0, v97, vcc
	v_add_co_u32_e32 v102, vcc, s10, v96
	s_nop 1
	v_addc_co_u32_e32 v103, vcc, 0, v97, vcc
	v_add_co_u32_e32 v104, vcc, s11, v96
	s_nop 1
	v_addc_co_u32_e32 v105, vcc, 0, v97, vcc
	v_add_co_u32_e32 v106, vcc, s12, v96
	s_nop 1
	v_addc_co_u32_e32 v107, vcc, 0, v97, vcc
	v_add_co_u32_e32 v108, vcc, s13, v96
	s_nop 1
	v_addc_co_u32_e32 v109, vcc, 0, v97, vcc
	v_add_co_u32_e32 v110, vcc, s14, v96
	s_nop 1
	v_addc_co_u32_e32 v111, vcc, 0, v97, vcc
	v_mov_b32_e32 v67, s18
	s_add_i32 s18, s18, 32
	ds_read_b128 v[50:53], v67
	ds_read_b128 v[54:57], v67 offset:16
	ds_read_b128 v[58:61], v67 offset:8192
	ds_read_b128 v[62:65], v67 offset:8208
	ds_read_b128 v[70:73], v67 offset:16384
	ds_read_b128 v[74:77], v67 offset:16400
	s_waitcnt lgkmcnt(5)
	v_mov_b32_e32 v78, v53
	s_waitcnt lgkmcnt(3)
	v_mov_b32_e32 v80, v61
	v_mov_b32_e32 v84, v57
	s_waitcnt lgkmcnt(1)
	v_mov_b32_e32 v82, v73
	v_mov_b32_e32 v86, v65
	s_waitcnt lgkmcnt(0)
	v_mov_b32_e32 v88, v77
	s_waitcnt vmcnt(7)
	v_pk_fma_f32 v[8:9], v[20:21], v[50:51], v[8:9] op_sel_hi:[1,0,1]
	v_pk_fma_f32 v[6:7], v[18:19], v[50:51], v[6:7] op_sel_hi:[1,0,1]
	v_pk_fma_f32 v[12:13], v[20:21], v[58:59], v[12:13] op_sel_hi:[1,0,1]
	v_pk_fma_f32 v[10:11], v[18:19], v[58:59], v[10:11] op_sel_hi:[1,0,1]
	v_pk_fma_f32 v[4:5], v[20:21], v[70:71], v[4:5] op_sel_hi:[1,0,1]
	v_pk_fma_f32 v[2:3], v[18:19], v[70:71], v[2:3] op_sel_hi:[1,0,1]
	global_load_dwordx4 v[18:21], v[96:97], off nt
	s_waitcnt vmcnt(7)
	v_pk_fma_f32 v[6:7], v[22:23], v[50:51], v[6:7] op_sel:[0,1,0]
	v_pk_fma_f32 v[8:9], v[24:25], v[50:51], v[8:9] op_sel:[0,1,0]
	v_pk_fma_f32 v[10:11], v[22:23], v[58:59], v[10:11] op_sel:[0,1,0]
	v_pk_fma_f32 v[12:13], v[24:25], v[58:59], v[12:13] op_sel:[0,1,0]
	v_pk_fma_f32 v[2:3], v[22:23], v[70:71], v[2:3] op_sel:[0,1,0]
	v_pk_fma_f32 v[4:5], v[24:25], v[70:71], v[4:5] op_sel:[0,1,0]
	global_load_dwordx4 v[22:25], v[98:99], off nt
	s_waitcnt vmcnt(7)
	v_pk_fma_f32 v[8:9], v[28:29], v[52:53], v[8:9] op_sel_hi:[1,0,1]
	v_pk_fma_f32 v[6:7], v[26:27], v[52:53], v[6:7] op_sel_hi:[1,0,1]
	v_pk_fma_f32 v[12:13], v[28:29], v[60:61], v[12:13] op_sel_hi:[1,0,1]
	v_pk_fma_f32 v[10:11], v[26:27], v[60:61], v[10:11] op_sel_hi:[1,0,1]
	v_pk_fma_f32 v[4:5], v[28:29], v[72:73], v[4:5] op_sel_hi:[1,0,1]
	v_pk_fma_f32 v[2:3], v[26:27], v[72:73], v[2:3] op_sel_hi:[1,0,1]
	global_load_dwordx4 v[26:29], v[100:101], off nt
	s_waitcnt vmcnt(7)
	v_pk_fma_f32 v[8:9], v[32:33], v[78:79], v[8:9] op_sel_hi:[1,0,1]
	v_pk_fma_f32 v[6:7], v[30:31], v[78:79], v[6:7] op_sel_hi:[1,0,1]
	v_pk_fma_f32 v[12:13], v[32:33], v[80:81], v[12:13] op_sel_hi:[1,0,1]
	v_pk_fma_f32 v[10:11], v[30:31], v[80:81], v[10:11] op_sel_hi:[1,0,1]
	v_pk_fma_f32 v[4:5], v[32:33], v[82:83], v[4:5] op_sel_hi:[1,0,1]
	v_pk_fma_f32 v[2:3], v[30:31], v[82:83], v[2:3] op_sel_hi:[1,0,1]
	global_load_dwordx4 v[30:33], v[102:103], off nt
	s_waitcnt vmcnt(7)
; __device__ __forceinline__ void p0a(Frame& F, const Args& AR) {
;     ...
;             for (int d = 0; d < DCH; ++d) { const f32x4 w = __builtin_nontemporal_load((const f32x4*)(wp + (size_t)d * MODW)); const int dd = ch * DCH + d;
;                 a0 += w * sv[dd]; a1 += w * sv[DM + dd]; a2 += w * sv[2 * DM + dd]; }
;             float* o = modp + ((size_t)(ch * DEPTH + l) * 3) * MODW + jg * 2048 + F.tid * 4;
;             *(f32x4*)(o) = a0; *(f32x4*)(o + MODW) = a1; *(f32x4*)(o + 2 * MODW) = a2;
	v_pk_fma_f32 v[8:9], v[36:37], v[54:55], v[8:9] op_sel_hi:[1,0,1]
	v_pk_fma_f32 v[6:7], v[34:35], v[54:55], v[6:7] op_sel_hi:[1,0,1]
	v_pk_fma_f32 v[12:13], v[36:37], v[62:63], v[12:13] op_sel_hi:[1,0,1]
	v_pk_fma_f32 v[10:11], v[34:35], v[62:63], v[10:11] op_sel_hi:[1,0,1]
	v_pk_fma_f32 v[4:5], v[36:37], v[74:75], v[4:5] op_sel_hi:[1,0,1]
	v_pk_fma_f32 v[2:3], v[34:35], v[74:75], v[2:3] op_sel_hi:[1,0,1]
	global_load_dwordx4 v[34:37], v[104:105], off nt
	s_waitcnt vmcnt(7)
	v_pk_fma_f32 v[8:9], v[40:41], v[54:55], v[8:9] op_sel:[0,1,0]
	v_pk_fma_f32 v[6:7], v[38:39], v[54:55], v[6:7] op_sel:[0,1,0]
	v_pk_fma_f32 v[12:13], v[40:41], v[62:63], v[12:13] op_sel:[0,1,0]
	v_pk_fma_f32 v[10:11], v[38:39], v[62:63], v[10:11] op_sel:[0,1,0]
	v_pk_fma_f32 v[4:5], v[40:41], v[74:75], v[4:5] op_sel:[0,1,0]
	v_pk_fma_f32 v[2:3], v[38:39], v[74:75], v[2:3] op_sel:[0,1,0]
	global_load_dwordx4 v[38:41], v[106:107], off nt
	s_waitcnt vmcnt(7)
	v_pk_fma_f32 v[8:9], v[44:45], v[56:57], v[8:9] op_sel_hi:[1,0,1]
	v_pk_fma_f32 v[6:7], v[42:43], v[56:57], v[6:7] op_sel_hi:[1,0,1]
	v_pk_fma_f32 v[12:13], v[44:45], v[64:65], v[12:13] op_sel_hi:[1,0,1]
	v_pk_fma_f32 v[10:11], v[42:43], v[64:65], v[10:11] op_sel_hi:[1,0,1]
	v_pk_fma_f32 v[4:5], v[44:45], v[76:77], v[4:5] op_sel_hi:[1,0,1]
	v_pk_fma_f32 v[2:3], v[42:43], v[76:77], v[2:3] op_sel_hi:[1,0,1]
	global_load_dwordx4 v[42:45], v[108:109], off nt
	s_waitcnt vmcnt(7)
	v_pk_fma_f32 v[8:9], v[48:49], v[84:85], v[8:9] op_sel_hi:[1,0,1]
	v_pk_fma_f32 v[6:7], v[46:47], v[84:85], v[6:7] op_sel_hi:[1,0,1]
	v_pk_fma_f32 v[12:13], v[48:49], v[86:87], v[12:13] op_sel_hi:[1,0,1]
	v_pk_fma_f32 v[10:11], v[46:47], v[86:87], v[10:11] op_sel_hi:[1,0,1]
	v_pk_fma_f32 v[4:5], v[48:49], v[88:89], v[4:5] op_sel_hi:[1,0,1]
	v_pk_fma_f32 v[2:3], v[46:47], v[88:89], v[2:3] op_sel_hi:[1,0,1]
	global_load_dwordx4 v[46:49], v[110:111], off nt
	s_branch .LBB0_30
.Lgemv_tail:
	v_mov_b32_e32 v67, s18
	s_add_i32 s18, s18, 32
	ds_read_b128 v[50:53], v67
	ds_read_b128 v[54:57], v67 offset:16
	ds_read_b128 v[58:61], v67 offset:8192
	ds_read_b128 v[62:65], v67 offset:8208
	ds_read_b128 v[70:73], v67 offset:16384
	ds_read_b128 v[74:77], v67 offset:16400
	s_waitcnt lgkmcnt(5)
	v_mov_b32_e32 v78, v53
	s_waitcnt lgkmcnt(3)
	v_mov_b32_e32 v80, v61
	v_mov_b32_e32 v84, v57
	s_waitcnt lgkmcnt(1)
	v_mov_b32_e32 v82, v73
	v_mov_b32_e32 v86, v65
	s_waitcnt lgkmcnt(0)
	v_mov_b32_e32 v88, v77
	s_waitcnt vmcnt(7)
	v_pk_fma_f32 v[8:9], v[20:21], v[50:51], v[8:9] op_sel_hi:[1,0,1]
	v_pk_fma_f32 v[6:7], v[18:19], v[50:51], v[6:7] op_sel_hi:[1,0,1]
	v_pk_fma_f32 v[12:13], v[20:21], v[58:59], v[12:13] op_sel_hi:[1,0,1]
	v_pk_fma_f32 v[10:11], v[18:19], v[58:59], v[10:11] op_sel_hi:[1,0,1]
	v_pk_fma_f32 v[4:5], v[20:21], v[70:71], v[4:5] op_sel_hi:[1,0,1]
	v_pk_fma_f32 v[2:3], v[18:19], v[70:71], v[2:3] op_sel_hi:[1,0,1]
	s_waitcnt vmcnt(6)
	v_pk_fma_f32 v[6:7], v[22:23], v[50:51], v[6:7] op_sel:[0,1,0]
	v_pk_fma_f32 v[8:9], v[24:25], v[50:51], v[8:9] op_sel:[0,1,0]
	v_pk_fma_f32 v[10:11], v[22:23], v[58:59], v[10:11] op_sel:[0,1,0]
	v_pk_fma_f32 v[12:13], v[24:25], v[58:59], v[12:13] op_sel:[0,1,0]
	v_pk_fma_f32 v[2:3], v[22:23], v[70:71], v[2:3] op_sel:[0,1,0]
	v_pk_fma_f32 v[4:5], v[24:25], v[70:71], v[4:5] op_sel:[0,1,0]
	s_waitcnt vmcnt(5)
	v_pk_fma_f32 v[8:9], v[28:29], v[52:53], v[8:9] op_sel_hi:[1,0,1]
	v_pk_fma_f32 v[6:7], v[26:27], v[52:53], v[6:7] op_sel_hi:[1,0,1]
	v_pk_fma_f32 v[12:13], v[28:29], v[60:61], v[12:13] op_sel_hi:[1,0,1]
	v_pk_fma_f32 v[10:11], v[26:27], v[60:61], v[10:11] op_sel_hi:[1,0,1]
	v_pk_fma_f32 v[4:5], v[28:29], v[72:73], v[4:5] op_sel_hi:[1,0,1]
	v_pk_fma_f32 v[2:3], v[26:27], v[72:73], v[2:3] op_sel_hi:[1,0,1]
	s_waitcnt vmcnt(4)
	v_pk_fma_f32 v[8:9], v[32:33], v[78:79], v[8:9] op_sel_hi:[1,0,1]
	v_pk_fma_f32 v[6:7], v[30:31], v[78:79], v[6:7] op_sel_hi:[1,0,1]
	v_pk_fma_f32 v[12:13], v[32:33], v[80:81], v[12:13] op_sel_hi:[1,0,1]
	v_pk_fma_f32 v[10:11], v[30:31], v[80:81], v[10:11] op_sel_hi:[1,0,1]
	v_pk_fma_f32 v[4:5], v[32:33], v[82:83], v[4:5] op_sel_hi:[1,0,1]
	v_pk_fma_f32 v[2:3], v[30:31], v[82:83], v[2:3] op_sel_hi:[1,0,1]
	s_waitcnt vmcnt(3)
	v_pk_fma_f32 v[8:9], v[36:37], v[54:55], v[8:9] op_sel_hi:[1,0,1]
	v_pk_fma_f32 v[6:7], v[34:35], v[54:55], v[6:7] op_sel_hi:[1,0,1]
	v_pk_fma_f32 v[12:13], v[36:37], v[62:63], v[12:13] op_sel_hi:[1,0,1]
	v_pk_fma_f32 v[10:11], v[34:35], v[62:63], v[10:11] op_sel_hi:[1,0,1]
	v_pk_fma_f32 v[4:5], v[36:37], v[74:75], v[4:5] op_sel_hi:[1,0,1]
	v_pk_fma_f32 v[2:3], v[34:35], v[74:75], v[2:3] op_sel_hi:[1,0,1]
	s_waitcnt vmcnt(2)
	v_pk_fma_f32 v[8:9], v[40:41], v[54:55], v[8:9] op_sel:[0,1,0]
	v_pk_fma_f32 v[6:7], v[38:39], v[54:55], v[6:7] op_sel:[0,1,0]
	v_pk_fma_f32 v[12:13], v[40:41], v[62:63], v[12:13] op_sel:[0,1,0]
	v_pk_fma_f32 v[10:11], v[38:39], v[62:63], v[10:11] op_sel:[0,1,0]
	v_pk_fma_f32 v[4:5], v[40:41], v[74:75], v[4:5] op_sel:[0,1,0]
	v_pk_fma_f32 v[2:3], v[38:39], v[74:75], v[2:3] op_sel:[0,1,0]
	s_waitcnt vmcnt(1)
	v_pk_fma_f32 v[8:9], v[44:45], v[56:57], v[8:9] op_sel_hi:[1,0,1]
	v_pk_fma_f32 v[6:7], v[42:43], v[56:57], v[6:7] op_sel_hi:[1,0,1]
	v_pk_fma_f32 v[12:13], v[44:45], v[64:65], v[12:13] op_sel_hi:[1,0,1]
	v_pk_fma_f32 v[10:11], v[42:43], v[64:65], v[10:11] op_sel_hi:[1,0,1]
	v_pk_fma_f32 v[4:5], v[44:45], v[76:77], v[4:5] op_sel_hi:[1,0,1]
	v_pk_fma_f32 v[2:3], v[42:43], v[76:77], v[2:3] op_sel_hi:[1,0,1]
	s_waitcnt vmcnt(0)
	v_pk_fma_f32 v[8:9], v[48:49], v[84:85], v[8:9] op_sel_hi:[1,0,1]
	v_pk_fma_f32 v[6:7], v[46:47], v[84:85], v[6:7] op_sel_hi:[1,0,1]
	v_pk_fma_f32 v[12:13], v[48:49], v[86:87], v[12:13] op_sel_hi:[1,0,1]
	v_pk_fma_f32 v[10:11], v[46:47], v[86:87], v[10:11] op_sel_hi:[1,0,1]
	v_pk_fma_f32 v[4:5], v[48:49], v[88:89], v[4:5] op_sel_hi:[1,0,1]
	v_pk_fma_f32 v[2:3], v[46:47], v[88:89], v[2:3] op_sel_hi:[1,0,1]
	s_lshl_b32 s4, s16, 2
	s_add_i32 s4, s4, s17
	s_mul_i32 s5, s4, 3
	s_mul_i32 s4, s4, 0x36000
	s_mul_hi_i32 s5, s5, 0x12000
	s_add_u32 s4, s6, s4
	s_addc_u32 s5, s7, s5
	s_add_u32 s0, s4, s0
	s_addc_u32 s1, s5, s1
	v_lshl_add_u64 v[16:17], v[14:15], 2, s[0:1]
	global_store_dwordx4 v[16:17], v[6:9], off
	s_add_i32 s15, s15, s33
	s_cmpk_gt_i32 s15, 0x47f
	v_add_co_u32_e32 v6, vcc, 0x12000, v16
	s_nop 1
	v_addc_co_u32_e32 v7, vcc, 0, v17, vcc
	global_store_dwordx4 v[6:7], v[10:13], off
	v_add_co_u32_e32 v6, vcc, 0x24000, v16
	s_nop 1
	v_addc_co_u32_e32 v7, vcc, 0, v17, vcc
	global_store_dwordx4 v[6:7], v[2:5], off
	s_cbranch_scc0 .LBB0_29
